# mout: GEMM2 (Q x Ct) initial 14 LDS-DMA stage loads issued right after GEMM1, overlapping the P epilogue; on top of v54
# baseline (speedup 1.0000x reference)
.LBB0_639:
	s_lshl_b64 s[98:99], s[18:19], 17
	s_add_u32 s98, s98, s45
	s_addc_u32 s99, s99, s52
	v_readfirstlane_b32 s97, v182
	v_and_b32_e32 v240, 63, v182
	v_lshrrev_b32_e32 v241, 6, v182
	s_lshr_b32 s97, s97, 6
	s_lshl_b32 s97, s97, 10
	v_and_b32_e32 v242, 3, v240
	v_lshlrev_b32_e32 v242, 4, v242
	v_lshrrev_b32_e32 v243, 5, v240
	v_lshlrev_b32_e32 v243, 5, v243
	v_xor_b32_e32 v242, v242, v243
	v_and_b32_e32 v243, 1, v241
	v_lshl_or_b32 v242, v243, 6, v242
	v_lshrrev_b32_e32 v243, 1, v241
	v_lshrrev_b32_e32 v244, 2, v240
	v_lshl_add_u32 v245, v243, 4, v244
	v_lshl_add_u32 v246, v245, 11, v242
	v_add_u32_e32 v247, 0x20000, v246
	v_lshrrev_b32_e32 v248, 2, v241
	v_lshlrev_b32_e32 v248, 5, v248
	v_lshrrev_b32_e32 v249, 4, v240
	v_lshl_add_u32 v248, v249, 3, v248
	v_and_b32_e32 v249, 1, v243
	v_lshl_add_u32 v248, v249, 2, v248
	v_and_b32_e32 v249, 3, v244
	v_add_u32_e32 v248, v248, v249
	v_lshl_add_u32 v248, v248, 9, v242
	v_add_u32_e32 v249, 0x8000, v248
	s_add_i32 m0, s97, 0x10000
	s_add_u32 s28, s98, 0x10000
	global_load_lds_dwordx4 v248, s[98:99]
	s_add_i32 m0, s97, 0x12000
	s_addc_u32 s29, s99, 0
	global_load_lds_dwordx4 v249, s[98:99]
	s_mov_b32 m0, s97
	s_nop 0
	global_load_lds_dwordx4 v246, s[24:25]
	s_add_i32 m0, s97, 0x2000
	s_nop 0
	global_load_lds_dwordx4 v247, s[24:25]
	s_add_i32 m0, s97, 0x14000
	s_nop 0
	global_load_lds_dwordx4 v248, s[28:29]
	s_add_i32 m0, s97, 0x16000
	s_nop 0
	global_load_lds_dwordx4 v249, s[28:29]
	s_add_u32 s30, s24, 0x40000
	s_addc_u32 s31, s25, 0
	s_add_i32 m0, s97, 0x4000
	s_nop 0
	global_load_lds_dwordx4 v246, s[30:31]
	s_add_i32 m0, s97, 0x6000
	s_nop 0
	global_load_lds_dwordx4 v247, s[30:31]
	s_add_u32 s30, s98, 0x80
	s_addc_u32 s31, s99, 0
	s_add_i32 m0, s97, 0x18000
	s_nop 0
	global_load_lds_dwordx4 v248, s[30:31]
	s_add_i32 m0, s97, 0x1a000
	s_nop 0
	global_load_lds_dwordx4 v249, s[30:31]
	s_add_u32 s30, s24, 0x80
	s_addc_u32 s31, s25, 0
	s_add_i32 m0, s97, 0x8000
	s_nop 0
	global_load_lds_dwordx4 v246, s[30:31]
	s_add_i32 m0, s97, 0xa000
	s_nop 0
	global_load_lds_dwordx4 v247, s[30:31]
	s_add_u32 s30, s28, 0x80
	s_addc_u32 s31, s29, 0
	s_add_i32 m0, s97, 0x1c000
	s_nop 0
	global_load_lds_dwordx4 v248, s[30:31]
	s_add_i32 m0, s97, 0x1e000
	s_nop 0
	global_load_lds_dwordx4 v249, s[30:31]
	v_and_b32_e32 v131, 64, v183
	s_and_b32 s42, s2, 3
	s_lshl_b64 s[0:1], s[18:19], 17
	v_xor_b32_e32 v130, 16, v183
	v_add_u32_e32 v131, 64, v131
	v_mov_b32_e32 v128, v182
	s_add_u32 s22, s41, s0
	v_cmp_lt_i32_e32 vcc, v130, v131
	s_addc_u32 s23, s44, s1
	v_and_b32_e32 v129, 63, v128
	s_ashr_i32 s79, s81, 2
	v_cndmask_b32_e32 v130, v183, v130, vcc
	s_andn2_b32 s79, s79, 63
	v_ashrrev_i32_e32 v128, 1, v129
	v_lshlrev_b32_e32 v172, 2, v130
	v_xor_b32_e32 v130, 32, v183
	v_and_or_b32 v132, v129, 15, s79
	s_lshl_b32 s80, s42, 5
	v_and_b32_e32 v128, -8, v128
	v_cmp_lt_i32_e32 vcc, v130, v131
	v_add_u32_e32 v128, s80, v128
	s_mov_b64 s[26:27], s[22:23]
	v_cndmask_b32_e32 v130, v183, v130, vcc
	v_cmp_gt_u32_e32 vcc, 16, v129
	v_lshl_add_u32 v129, v132, 2, 0
	v_add_u32_e32 v135, 0x20000, v129
	v_lshl_add_u32 v129, v128, 2, 0
	v_add_u32_e32 v134, 0x20800, v129
	ds_read_b32 v150, v135
	ds_read_b128 v[136:139], v134
	ds_read_b128 v[140:143], v134 offset:16
	s_lshl_b32 s0, s42, 10
	v_ashrrev_i32_e32 v133, 31, v132
	v_lshlrev_b32_e32 v173, 2, v130
	s_add_i32 s2, s0, 0
	v_lshlrev_b64 v[130:131], 9, v[132:133]
	v_cmp_gt_i32_e64 s[0:1], v128, v132
	v_lshl_add_u64 v[144:145], s[26:27], 0, v[130:131]
	s_waitcnt lgkmcnt(0)
	v_sub_f32_e32 v129, v136, v150
	v_cndmask_b32_e64 v130, 1.0, 0, s[0:1]
	v_mul_f32_e32 v130, v124, v130
	v_sub_f32_e32 v124, v140, v150
	v_min_f32_e32 v124, 0, v124
	v_mul_f32_e32 v124, 0x3fb8aa3b, v124
	v_exp_f32_e32 v136, v124
	v_sub_f32_e32 v124, v137, v150
	v_sub_f32_e32 v137, v141, v150
	v_min_f32_e32 v124, 0, v124
	v_min_f32_e32 v137, 0, v137
	v_min_f32_e32 v129, 0, v129
	v_cmp_lt_i32_e64 s[0:1], v128, v132
	v_mul_f32_e32 v124, 0x3fb8aa3b, v124
	v_or_b32_e32 v131, 5, v128
	v_mul_f32_e32 v137, 0x3fb8aa3b, v137
	v_mul_f32_e32 v129, 0x3fb8aa3b, v129
	v_cndmask_b32_e64 v140, 0, 1.0, s[0:1]
	v_exp_f32_e32 v146, v124
	v_or_b32_e32 v124, 4, v128
	v_exp_f32_e32 v137, v137
	v_cmp_gt_i32_e64 s[0:1], v131, v132
	v_exp_f32_e32 v129, v129
	v_mul_f32_e32 v125, v125, v140
	v_cndmask_b32_e64 v141, 1.0, 0, s[0:1]
	v_cmp_gt_i32_e64 s[0:1], v124, v132
	v_mul_f32_e32 v133, v130, v129
	v_mul_f32_e32 v148, v125, v146
	v_cndmask_b32_e64 v140, 1.0, 0, s[0:1]
	v_pk_mul_f32 v[120:121], v[120:121], v[140:141]
	s_add_i32 s2, s2, 0x21400
	v_pk_mul_f32 v[140:141], v[120:121], v[136:137]
	s_nop 0
	v_fma_f32 v120, v130, v129, v140
	v_add_f32_e32 v120, 0, v120
	v_fma_f32 v121, v125, v146, v141
	v_add_f32_e32 v149, v121, v120
	v_sub_f32_e32 v120, v138, v150
	v_sub_f32_e32 v129, v139, v150
	v_min_f32_e32 v120, 0, v120
	v_min_f32_e32 v129, 0, v129
	v_mul_f32_e32 v120, 0x3fb8aa3b, v120
	v_mul_f32_e32 v129, 0x3fb8aa3b, v129
	v_exp_f32_e32 v136, v120
	v_sub_f32_e32 v120, v142, v150
	v_or_b32_e32 v125, 3, v128
	v_exp_f32_e32 v137, v129
	v_sub_f32_e32 v129, v143, v150
	v_min_f32_e32 v120, 0, v120
	v_or_b32_e32 v130, 2, v128
	v_cmp_gt_i32_e64 s[0:1], v125, v132
	v_min_f32_e32 v129, 0, v129
	v_mul_f32_e32 v120, 0x3fb8aa3b, v120
	v_or_b32_e32 v121, 7, v128
	v_cndmask_b32_e64 v147, 1.0, 0, s[0:1]
	v_cmp_gt_i32_e64 s[0:1], v130, v132
	v_mul_f32_e32 v129, 0x3fb8aa3b, v129
	v_exp_f32_e32 v138, v120
	v_or_b32_e32 v120, 6, v128
	v_cndmask_b32_e64 v146, 1.0, 0, s[0:1]
	v_exp_f32_e32 v139, v129
	v_cmp_gt_i32_e64 s[0:1], v121, v132
	v_pk_mul_f32 v[126:127], v[126:127], v[146:147]
	v_ashrrev_i32_e32 v129, 31, v128
	v_cndmask_b32_e64 v143, 1.0, 0, s[0:1]
	v_cmp_gt_i32_e64 s[0:1], v120, v132
	v_pk_mul_f32 v[146:147], v[126:127], v[136:137]
	v_lshl_add_u64 v[144:145], v[128:129], 1, v[144:145]
	v_cndmask_b32_e64 v142, 1.0, 0, s[0:1]
	v_pk_mul_f32 v[122:123], v[122:123], v[142:143]
	s_nop 0
	v_pk_mul_f32 v[122:123], v[122:123], v[138:139]
	v_cvt_pk_bf16_f32 v138, v140, v141
	v_pk_fma_f32 v[126:127], v[126:127], v[136:137], v[122:123]
	v_cvt_pk_bf16_f32 v136, v133, v148
	v_cvt_pk_bf16_f32 v137, v146, v147
	v_cvt_pk_bf16_f32 v139, v122, v123
	global_store_dwordx4 v[144:145], v[136:139], off
	ds_read_b128 v[136:139], v134 offset:512
	ds_read_b128 v[140:143], v134 offset:528
	v_add_f32_e32 v122, v126, v149
	v_add_u32_e32 v126, 0x80, v128
	v_add_f32_e32 v127, v127, v122
	s_waitcnt lgkmcnt(0)
	v_sub_f32_e32 v122, v136, v150
	v_cmp_gt_i32_e64 s[0:1], v132, v126
	v_min_f32_e32 v122, 0, v122
	v_mul_f32_e32 v122, 0x3fb8aa3b, v122
	v_cndmask_b32_e64 v147, 0, 1.0, s[0:1]
	v_cmp_gt_i32_e64 s[0:1], v126, v132
	v_exp_f32_e32 v136, v122
	v_sub_f32_e32 v122, v140, v150
	v_cndmask_b32_e64 v146, 1.0, 0, s[0:1]
	v_pk_mul_f32 v[146:147], v[116:117], v[146:147]
	v_sub_f32_e32 v116, v141, v150
	v_min_f32_e32 v122, 0, v122
	v_sub_f32_e32 v133, v137, v150
	v_min_f32_e32 v116, 0, v116
	v_mul_f32_e32 v122, 0x3fb8aa3b, v122
	v_or_b32_e32 v123, 5, v126
	v_min_f32_e32 v133, 0, v133
	v_mul_f32_e32 v116, 0x3fb8aa3b, v116
	v_exp_f32_e32 v140, v122
	v_or_b32_e32 v122, 4, v126
	v_mul_f32_e32 v133, 0x3fb8aa3b, v133
	v_exp_f32_e32 v141, v116
	v_cmp_gt_i32_e64 s[0:1], v123, v132
	v_exp_f32_e32 v137, v133
	v_sub_f32_e32 v133, v139, v150
	v_cndmask_b32_e64 v117, 1.0, 0, s[0:1]
	v_cmp_gt_i32_e64 s[0:1], v122, v132
	v_min_f32_e32 v133, 0, v133
	v_mul_f32_e32 v133, 0x3fb8aa3b, v133
	v_cndmask_b32_e64 v116, 1.0, 0, s[0:1]
	v_pk_mul_f32 v[112:113], v[112:113], v[116:117]
	v_or_b32_e32 v117, 3, v126
	v_pk_mul_f32 v[140:141], v[112:113], v[140:141]
	v_exp_f32_e32 v139, v133
	v_pk_fma_f32 v[112:113], v[146:147], v[136:137], v[140:141]
	v_sub_f32_e32 v133, v143, v150
	v_add_f32_e32 v112, v112, v127
	v_add_f32_e32 v127, v113, v112
	v_sub_f32_e32 v112, v138, v150
	v_min_f32_e32 v112, 0, v112
	v_mul_f32_e32 v112, 0x3fb8aa3b, v112
	v_exp_f32_e32 v138, v112
	v_sub_f32_e32 v112, v142, v150
	v_min_f32_e32 v112, 0, v112
	v_or_b32_e32 v116, 2, v126
	v_cmp_gt_i32_e64 s[0:1], v117, v132
	v_min_f32_e32 v133, 0, v133
	v_mul_f32_e32 v112, 0x3fb8aa3b, v112
	v_or_b32_e32 v113, 7, v126
	v_cndmask_b32_e64 v149, 1.0, 0, s[0:1]
	v_cmp_gt_i32_e64 s[0:1], v116, v132
	v_mul_f32_e32 v133, 0x3fb8aa3b, v133
	v_exp_f32_e32 v142, v112
	v_or_b32_e32 v112, 6, v126
	v_cndmask_b32_e64 v148, 1.0, 0, s[0:1]
	v_exp_f32_e32 v143, v133
	v_cmp_gt_i32_e64 s[0:1], v113, v132
	v_pk_mul_f32 v[118:119], v[118:119], v[148:149]
	s_nop 0
	v_cndmask_b32_e64 v149, 1.0, 0, s[0:1]
	v_cmp_gt_i32_e64 s[0:1], v112, v132
	s_nop 1
	v_cndmask_b32_e64 v148, 1.0, 0, s[0:1]
	v_pk_mul_f32 v[114:115], v[114:115], v[148:149]
	s_nop 0
	v_pk_mul_f32 v[142:143], v[114:115], v[142:143]
	s_nop 0
	v_pk_fma_f32 v[114:115], v[118:119], v[138:139], v[142:143]
	v_pk_mul_f32 v[118:119], v[118:119], v[138:139]
	v_add_f32_e32 v114, v114, v127
	v_add_f32_e32 v127, v115, v114
	ds_bpermute_b32 v133, v172, v127
	v_pk_mul_f32 v[114:115], v[146:147], v[136:137]
	v_cvt_pk_bf16_f32 v137, v118, v119
	v_cvt_pk_bf16_f32 v136, v114, v115
	v_cvt_pk_bf16_f32 v138, v140, v141
	s_waitcnt lgkmcnt(0)
	v_add_f32_e32 v115, v127, v133
	ds_bpermute_b32 v118, v173, v115
	v_cvt_pk_bf16_f32 v139, v142, v143
	v_lshl_add_u32 v114, v132, 2, s2
	global_store_dwordx4 v[144:145], v[136:139], off offset:256
	s_and_saveexec_b64 s[0:1], vcc
	s_cbranch_execz .LBB0_641
	s_waitcnt lgkmcnt(0)
	v_add_f32_e32 v115, v115, v118
	ds_write_b32 v114, v115

.LBB0_655:
	s_or_b64 exec, exec, s[26:27]
	s_lshl_b64 s[0:1], s[0:1], 1
	s_add_u32 s26, s45, s0
	s_addc_u32 s27, s52, s1
	v_mov_b32_e32 v14, v182
	s_waitcnt vmcnt(0)
	s_waitcnt vmcnt(0) lgkmcnt(0)
	s_barrier
	s_nop 0
	v_bfe_i32 v2, v14, 27, 1
	v_lshlrev_b32_e32 v1, 4, v14
	v_lshrrev_b32_e32 v2, 22, v2
	v_add_u32_e32 v2, v1, v2
	v_and_b32_e32 v2, 0xfffffc00, v2
	v_sub_u32_e32 v2, v1, v2
	v_ashrrev_i32_e32 v0, 31, v14
	v_lshrrev_b32_e32 v3, 4, v2
	v_lshrrev_b32_e32 v0, 26, v0
	v_bitop3_b32 v3, v3, v2, 32 bitop3:0x6c
	v_ashrrev_i32_e32 v2, 31, v2
	v_add_u32_e32 v0, v14, v0
	v_lshrrev_b32_e32 v2, 26, v2
	v_ashrrev_i32_e32 v0, 6, v0
	v_add_u32_e32 v2, v3, v2
	v_lshlrev_b32_e32 v4, 3, v0
	v_ashrrev_i32_e32 v2, 6, v2
	v_and_b32_e32 v4, -16, v4
	v_mul_i32_i24_e32 v5, 64, v2
	v_add_u32_e32 v4, v2, v4
	v_sub_u32_e32 v3, v3, v5
	v_lshlrev_b32_e32 v0, 5, v0
	v_ashrrev_i16_sdwa v3, v184, sext(v3) dst_sel:DWORD dst_unused:UNUSED_PAD src0_sel:DWORD src1_sel:BYTE_0
	v_lshlrev_b32_e32 v5, 1, v4
	v_lshrrev_b32_e32 v6, 2, v4
	v_and_b32_e32 v2, 3, v2
	v_and_b32_e32 v0, 32, v0
	v_bfe_i32 v3, v3, 0, 16
	v_and_b32_e32 v5, 24, v5
	v_and_b32_e32 v6, 4, v6
	v_and_or_b32 v2, v4, s76, v2
	v_or3_b32 v2, v2, v6, v5
	v_add_lshl_u32 v3, v0, v3, 1
	v_add_u32_e32 v1, 0x2000, v1
	v_lshl_add_u32 v152, v2, 9, v3
	v_ashrrev_i32_e32 v2, 31, v1
	v_lshrrev_b32_e32 v2, 22, v2
	v_add_u32_e32 v2, v1, v2
	v_ashrrev_i32_e32 v2, 10, v2
	v_lshl_add_u32 v0, v4, 11, v3
	v_mul_i32_i24_e32 v3, 0x400, v2
	v_sub_u32_e32 v1, v1, v3
	v_lshrrev_b32_e32 v3, 4, v1
	v_bitop3_b32 v1, v3, v1, 32 bitop3:0x6c
	v_ashrrev_i32_e32 v4, 31, v1
	v_lshrrev_b32_e32 v4, 26, v4
	v_lshlrev_b32_e32 v3, 3, v2
	v_add_u32_e32 v4, v1, v4
	v_readfirstlane_b32 s2, v14
	v_and_b32_e32 v3, -16, v3
	v_ashrrev_i32_e32 v5, 6, v4
	v_and_b32_e32 v4, 0xc0, v4
	v_add_u32_e32 v3, v5, v3
	v_sub_u32_e32 v1, v1, v4
	s_ashr_i32 s19, s2, 6
	v_lshlrev_b32_e32 v2, 5, v2
	v_ashrrev_i16_sdwa v1, v184, sext(v1) dst_sel:DWORD dst_unused:UNUSED_PAD src0_sel:DWORD src1_sel:BYTE_0
	v_lshlrev_b32_e32 v4, 1, v3
	v_lshrrev_b32_e32 v6, 2, v3
	v_and_b32_e32 v5, 3, v5
	s_lshl_b32 s85, s19, 10
	v_and_b32_e32 v2, 32, v2
	v_bfe_i32 v1, v1, 0, 16
	v_and_b32_e32 v4, 24, v4
	v_and_b32_e32 v6, 4, v6
	v_and_or_b32 v5, v3, s76, v5
	s_add_i32 s88, s85, 0
	v_or3_b32 v4, v5, v6, v4
	v_add_lshl_u32 v1, v2, v1, 1
	s_add_i32 m0, s88, 0x10000
	v_lshl_add_u32 v4, v4, 9, v1
	s_add_i32 m0, s88, 0x12000
	s_ashr_i32 s3, s2, 8
	s_mov_b32 m0, s88
	s_add_i32 s89, s88, 0x2000
	v_lshl_add_u32 v2, v3, 11, v1
	s_mov_b32 m0, s89
	s_add_u32 s28, s26, 0x10000
	s_addc_u32 s29, s27, 0
	s_add_i32 m0, s88, 0x14000
	v_mov_b32_e32 v5, v153
	s_add_i32 m0, s88, 0x16000
	v_mov_b32_e32 v1, v153
	s_add_u32 s28, s24, 0x40000
	s_addc_u32 s29, s25, 0
	s_add_i32 s87, s88, 0x4000
	s_mov_b32 m0, s87
	s_add_i32 s83, s88, 0x6000
	s_mov_b32 m0, s83
	v_mov_b32_e32 v3, v153
	v_lshl_add_u64 v[12:13], s[26:27], 0, v[152:153]
	v_lshl_add_u64 v[10:11], s[26:27], 0, v[4:5]
	v_lshl_add_u64 v[6:7], s[24:25], 0, v[0:1]
	s_cmp_eq_u32 s3, 1
	v_lshl_add_u64 v[8:9], s[24:25], 0, v[2:3]
	s_cbranch_scc0 .LBB0_657
	s_barrier
.LBB0_657:
	s_add_i32 s86, s74, s85
	s_lshl_b32 s19, s19, 12
	v_lshl_add_u64 v[16:17], v[12:13], 0, s[10:11]
	s_mov_b32 m0, s86
	s_add_i32 s84, s86, 0x2000
	s_lshl_b32 s30, s3, 13
	s_and_b32 s31, s19, 0x3000
	s_waitcnt vmcnt(4)
	s_barrier
	v_lshl_add_u64 v[16:17], v[10:11], 0, s[10:11]
	s_mov_b32 m0, s84
	s_add_i32 s51, s88, 0x8000
	s_add_i32 s49, s88, 0xa000
	v_lshl_add_u64 v[16:17], v[6:7], 0, s[10:11]
	s_mov_b32 m0, s51
	s_add_u32 s28, s26, 0x10080
	v_lshl_add_u64 v[16:17], v[8:9], 0, s[10:11]
	s_mov_b32 m0, s49
	s_addc_u32 s29, s27, 0
	s_add_i32 s3, s75, s85
	v_lshl_add_u64 v[16:17], s[28:29], 0, v[152:153]
	s_mov_b32 m0, s3
	s_add_i32 s19, s3, 0x2000
	v_lshl_add_u64 v[16:17], s[28:29], 0, v[4:5]
	s_mov_b32 m0, s19
	v_and_b32_e32 v15, 15, v14
	v_and_b32_e32 v16, 48, v14
	v_lshlrev_b32_e32 v14, 2, v14
	v_lshlrev_b32_e32 v15, 6, v15
	v_and_b32_e32 v14, 32, v14
	v_or_b32_e32 v17, v15, v16
	v_bitop3_b32 v15, v15, v14, v16 bitop3:0x36
	v_or_b32_e32 v64, s31, v15
	v_bitop3_b32 v14, v17, s30, v14 bitop3:0xde
	v_add_u32_e32 v170, s82, v64
	s_waitcnt vmcnt(6)
	s_barrier
	s_add_u32 s60, s24, 0x40080
	v_add_u32_e32 v185, 0, v14
	ds_read_b128 v[14:17], v170
	ds_read_b128 v[18:21], v170 offset:1024
	ds_read_b128 v[22:25], v170 offset:2048
	ds_read_b128 v[26:29], v170 offset:3072
	s_addc_u32 s61, s25, 0
	s_add_u32 s30, s26, 0x10100
	s_addc_u32 s31, s27, 0
	s_add_u32 s28, s24, 0x40100
	s_addc_u32 s29, s25, 0
	s_add_u32 s26, s26, 0x10180
	v_add_u32_e32 v171, s43, v64
	s_addc_u32 s27, s27, 0
	s_add_i32 s50, s88, 0xc000
	v_lshl_add_u64 v[62:63], s[60:61], 0, v[0:1]
	s_mov_b32 m0, s50
	s_add_i32 s48, s88, 0xe000
	ds_read_b128 v[30:33], v185
	ds_read_b128 v[34:37], v185 offset:1024
	ds_read_b128 v[38:41], v185 offset:2048
	ds_read_b128 v[42:45], v185 offset:3072
	ds_read_b128 v[46:49], v185 offset:4096
	ds_read_b128 v[50:53], v185 offset:5120
	ds_read_b128 v[54:57], v185 offset:6144
	ds_read_b128 v[58:61], v185 offset:7168
	global_load_lds_dwordx4 v[62:63], off
	v_lshl_add_u64 v[62:63], s[60:61], 0, v[2:3]
	s_mov_b32 m0, s48
	v_add_u32_e32 v234, s74, v64
	global_load_lds_dwordx4 v[62:63], off
	s_waitcnt lgkmcnt(8)
	s_barrier
	s_waitcnt lgkmcnt(0)
	v_add_u32_e32 v235, s75, v64
	s_setprio 1
	s_waitcnt lgkmcnt(0)
	v_mfma_f32_16x16x32_bf16 v[62:65], v[14:17], v[30:33], 0
	v_mfma_f32_16x16x32_bf16 v[66:69], v[22:25], v[30:33], 0
	v_mfma_f32_16x16x32_bf16 v[70:73], v[14:17], v[38:41], 0
	v_mfma_f32_16x16x32_bf16 v[74:77], v[22:25], v[38:41], 0
	v_mfma_f32_16x16x32_bf16 v[78:81], v[14:17], v[46:49], 0
	v_mfma_f32_16x16x32_bf16 v[82:85], v[22:25], v[46:49], 0
	v_mfma_f32_16x16x32_bf16 v[86:89], v[14:17], v[54:57], 0
	v_mfma_f32_16x16x32_bf16 v[90:93], v[22:25], v[54:57], 0
	v_mfma_f32_16x16x32_bf16 v[62:65], v[18:21], v[34:37], v[62:65]
	v_mfma_f32_16x16x32_bf16 v[66:69], v[26:29], v[34:37], v[66:69]
	v_mfma_f32_16x16x32_bf16 v[70:73], v[18:21], v[42:45], v[70:73]
	v_mfma_f32_16x16x32_bf16 v[74:77], v[26:29], v[42:45], v[74:77]
	v_mfma_f32_16x16x32_bf16 v[78:81], v[18:21], v[50:53], v[78:81]
	v_mfma_f32_16x16x32_bf16 v[82:85], v[26:29], v[50:53], v[82:85]
	v_mfma_f32_16x16x32_bf16 v[86:89], v[18:21], v[58:61], v[86:89]
	v_mfma_f32_16x16x32_bf16 v[90:93], v[26:29], v[58:61], v[90:93]
	s_setprio 0
	s_barrier
	s_add_i32 s60, s82, s85
	v_lshl_add_u64 v[110:111], v[12:13], 0, s[12:13]
	s_mov_b32 m0, s60
	ds_read_b128 v[94:97], v171
	ds_read_b128 v[98:101], v171 offset:1024
	ds_read_b128 v[102:105], v171 offset:2048
	ds_read_b128 v[106:109], v171 offset:3072
	global_load_lds_dwordx4 v[110:111], off
	v_lshl_add_u64 v[110:111], v[10:11], 0, s[12:13]
	s_add_i32 m0, s60, 0x2000
	s_nop 0
	global_load_lds_dwordx4 v[110:111], off
	s_barrier
	s_waitcnt lgkmcnt(0)
	s_setprio 1
	s_waitcnt lgkmcnt(0)
	v_mfma_f32_16x16x32_bf16 v[110:113], v[94:97], v[30:33], 0
	v_mfma_f32_16x16x32_bf16 v[30:33], v[102:105], v[30:33], 0
	v_mfma_f32_16x16x32_bf16 v[110:113], v[98:101], v[34:37], v[110:113]
	v_mfma_f32_16x16x32_bf16 v[30:33], v[106:109], v[34:37], v[30:33]
	v_mfma_f32_16x16x32_bf16 v[34:37], v[94:97], v[38:41], 0
	v_mfma_f32_16x16x32_bf16 v[38:41], v[102:105], v[38:41], 0
	v_mfma_f32_16x16x32_bf16 v[34:37], v[98:101], v[42:45], v[34:37]
	v_mfma_f32_16x16x32_bf16 v[38:41], v[106:109], v[42:45], v[38:41]
	v_mfma_f32_16x16x32_bf16 v[42:45], v[94:97], v[46:49], 0
	v_mfma_f32_16x16x32_bf16 v[46:49], v[102:105], v[46:49], 0
	v_mfma_f32_16x16x32_bf16 v[42:45], v[98:101], v[50:53], v[42:45]
	v_mfma_f32_16x16x32_bf16 v[46:49], v[106:109], v[50:53], v[46:49]
	v_mfma_f32_16x16x32_bf16 v[50:53], v[94:97], v[54:57], 0
	v_mfma_f32_16x16x32_bf16 v[54:57], v[102:105], v[54:57], 0
	v_mfma_f32_16x16x32_bf16 v[50:53], v[98:101], v[58:61], v[50:53]
	v_mfma_f32_16x16x32_bf16 v[54:57], v[106:109], v[58:61], v[54:57]
	s_setprio 0
	s_mov_b32 m0, s88
	v_lshl_add_u64 v[142:143], v[6:7], 0, s[12:13]
	s_barrier
	ds_read_b128 v[58:61], v185 offset:16384
	ds_read_b128 v[114:117], v185 offset:17408
	ds_read_b128 v[118:121], v185 offset:18432
	ds_read_b128 v[122:125], v185 offset:19456
	ds_read_b128 v[126:129], v185 offset:20480
	ds_read_b128 v[130:133], v185 offset:21504
	ds_read_b128 v[134:137], v185 offset:22528
	ds_read_b128 v[138:141], v185 offset:23552
	global_load_lds_dwordx4 v[142:143], off
	v_lshl_add_u64 v[142:143], v[8:9], 0, s[12:13]
	s_mov_b32 m0, s89
	s_nop 0
	global_load_lds_dwordx4 v[142:143], off
	s_barrier
	s_waitcnt lgkmcnt(0)
	s_setprio 1
	s_waitcnt lgkmcnt(0)
	v_mfma_f32_16x16x32_bf16 v[142:145], v[14:17], v[58:61], 0
	v_mfma_f32_16x16x32_bf16 v[154:157], v[14:17], v[118:121], 0
	v_mfma_f32_16x16x32_bf16 v[162:165], v[14:17], v[126:129], 0
	v_mfma_f32_16x16x32_bf16 v[14:17], v[14:17], v[134:137], 0
	v_mfma_f32_16x16x32_bf16 v[142:145], v[18:21], v[114:117], v[142:145]
	v_mfma_f32_16x16x32_bf16 v[154:157], v[18:21], v[122:125], v[154:157]
	v_mfma_f32_16x16x32_bf16 v[162:165], v[18:21], v[130:133], v[162:165]
	v_mfma_f32_16x16x32_bf16 v[14:17], v[18:21], v[138:141], v[14:17]
	v_mfma_f32_16x16x32_bf16 v[18:21], v[22:25], v[134:137], 0
	v_mfma_f32_16x16x32_bf16 v[146:149], v[22:25], v[58:61], 0
	v_mfma_f32_16x16x32_bf16 v[158:161], v[22:25], v[118:121], 0
	v_mfma_f32_16x16x32_bf16 v[166:169], v[22:25], v[126:129], 0
	v_mfma_f32_16x16x32_bf16 v[18:21], v[26:29], v[138:141], v[18:21]
	v_mfma_f32_16x16x32_bf16 v[146:149], v[26:29], v[114:117], v[146:149]
	v_mfma_f32_16x16x32_bf16 v[158:161], v[26:29], v[122:125], v[158:161]
	v_mfma_f32_16x16x32_bf16 v[166:169], v[26:29], v[130:133], v[166:169]
	s_setprio 0
	s_barrier
	s_add_i32 s60, s43, s85
	v_lshl_add_u64 v[22:23], s[30:31], 0, v[152:153]
	s_mov_b32 m0, s60
	s_nop 0
	global_load_lds_dwordx4 v[22:23], off
	v_lshl_add_u64 v[22:23], s[30:31], 0, v[4:5]
	s_add_i32 m0, s60, 0x2000
	s_nop 0
	global_load_lds_dwordx4 v[22:23], off
	s_waitcnt vmcnt(6)
	s_barrier
	s_setprio 1
	v_mfma_f32_16x16x32_bf16 v[22:25], v[94:97], v[58:61], 0
	v_mfma_f32_16x16x32_bf16 v[26:29], v[102:105], v[58:61], 0
	v_mfma_f32_16x16x32_bf16 v[22:25], v[98:101], v[114:117], v[22:25]
	v_mfma_f32_16x16x32_bf16 v[26:29], v[106:109], v[114:117], v[26:29]
	v_mfma_f32_16x16x32_bf16 v[58:61], v[94:97], v[118:121], 0
	v_mfma_f32_16x16x32_bf16 v[114:117], v[102:105], v[118:121], 0
	v_mfma_f32_16x16x32_bf16 v[118:121], v[94:97], v[126:129], 0
	v_mfma_f32_16x16x32_bf16 v[94:97], v[94:97], v[134:137], 0
	v_mfma_f32_16x16x32_bf16 v[58:61], v[98:101], v[122:125], v[58:61]
	v_mfma_f32_16x16x32_bf16 v[114:117], v[106:109], v[122:125], v[114:117]
	v_mfma_f32_16x16x32_bf16 v[118:121], v[98:101], v[130:133], v[118:121]
	v_mfma_f32_16x16x32_bf16 v[122:125], v[102:105], v[126:129], 0
	v_mfma_f32_16x16x32_bf16 v[94:97], v[98:101], v[138:141], v[94:97]
	v_mfma_f32_16x16x32_bf16 v[98:101], v[102:105], v[134:137], 0
	v_mfma_f32_16x16x32_bf16 v[122:125], v[106:109], v[130:133], v[122:125]
	v_mfma_f32_16x16x32_bf16 v[98:101], v[106:109], v[138:141], v[98:101]
	s_setprio 0
	s_barrier
	ds_read_b128 v[102:105], v234
	ds_read_b128 v[106:109], v234 offset:1024
	ds_read_b128 v[126:129], v234 offset:2048
	ds_read_b128 v[130:133], v234 offset:3072
	s_mov_b32 m0, s87
	v_lshl_add_u64 v[150:151], s[28:29], 0, v[0:1]
	ds_read_b128 v[134:137], v185 offset:32768
	ds_read_b128 v[138:141], v185 offset:33792
	ds_read_b128 v[174:177], v185 offset:34816
	ds_read_b128 v[178:181], v185 offset:35840
	ds_read_b128 v[186:189], v185 offset:36864
	ds_read_b128 v[190:193], v185 offset:37888
	ds_read_b128 v[194:197], v185 offset:38912
	ds_read_b128 v[198:201], v185 offset:39936
	global_load_lds_dwordx4 v[150:151], off
	v_lshl_add_u64 v[150:151], s[28:29], 0, v[2:3]
	s_mov_b32 m0, s83
	s_nop 0
	global_load_lds_dwordx4 v[150:151], off
	s_waitcnt lgkmcnt(8)
	s_barrier
	s_waitcnt lgkmcnt(0)
	s_setprio 1
	s_waitcnt lgkmcnt(0)
	v_mfma_f32_16x16x32_bf16 v[62:65], v[102:105], v[134:137], v[62:65]
	v_mfma_f32_16x16x32_bf16 v[66:69], v[126:129], v[134:137], v[66:69]
	v_mfma_f32_16x16x32_bf16 v[70:73], v[102:105], v[174:177], v[70:73]
	v_mfma_f32_16x16x32_bf16 v[74:77], v[126:129], v[174:177], v[74:77]
	v_mfma_f32_16x16x32_bf16 v[78:81], v[102:105], v[186:189], v[78:81]
	v_mfma_f32_16x16x32_bf16 v[82:85], v[126:129], v[186:189], v[82:85]
	v_mfma_f32_16x16x32_bf16 v[86:89], v[102:105], v[194:197], v[86:89]
	v_mfma_f32_16x16x32_bf16 v[90:93], v[126:129], v[194:197], v[90:93]
	v_mfma_f32_16x16x32_bf16 v[62:65], v[106:109], v[138:141], v[62:65]
	v_mfma_f32_16x16x32_bf16 v[66:69], v[130:133], v[138:141], v[66:69]
	v_mfma_f32_16x16x32_bf16 v[70:73], v[106:109], v[178:181], v[70:73]
	v_mfma_f32_16x16x32_bf16 v[74:77], v[130:133], v[178:181], v[74:77]
	v_mfma_f32_16x16x32_bf16 v[78:81], v[106:109], v[190:193], v[78:81]
	v_mfma_f32_16x16x32_bf16 v[82:85], v[130:133], v[190:193], v[82:85]
	v_mfma_f32_16x16x32_bf16 v[86:89], v[106:109], v[198:201], v[86:89]
	v_mfma_f32_16x16x32_bf16 v[90:93], v[130:133], v[198:201], v[90:93]
	s_setprio 0
	s_barrier
	s_mov_b32 m0, s86
	v_lshl_add_u64 v[12:13], v[12:13], 0, s[14:15]
	ds_read_b128 v[202:205], v235
	ds_read_b128 v[206:209], v235 offset:1024
	ds_read_b128 v[210:213], v235 offset:2048
	ds_read_b128 v[214:217], v235 offset:3072
	global_load_lds_dwordx4 v[12:13], off
	v_lshl_add_u64 v[10:11], v[10:11], 0, s[14:15]
	s_mov_b32 m0, s84
	s_nop 0
	global_load_lds_dwordx4 v[10:11], off
	s_barrier
	s_waitcnt lgkmcnt(0)
	s_setprio 1
	s_waitcnt lgkmcnt(0)
	v_mfma_f32_16x16x32_bf16 v[10:13], v[202:205], v[134:137], v[110:113]
	v_mfma_f32_16x16x32_bf16 v[30:33], v[210:213], v[134:137], v[30:33]
	v_mfma_f32_16x16x32_bf16 v[34:37], v[202:205], v[174:177], v[34:37]
	v_mfma_f32_16x16x32_bf16 v[38:41], v[210:213], v[174:177], v[38:41]
	v_mfma_f32_16x16x32_bf16 v[42:45], v[202:205], v[186:189], v[42:45]
	v_mfma_f32_16x16x32_bf16 v[46:49], v[210:213], v[186:189], v[46:49]
	v_mfma_f32_16x16x32_bf16 v[50:53], v[202:205], v[194:197], v[50:53]
	v_mfma_f32_16x16x32_bf16 v[54:57], v[210:213], v[194:197], v[54:57]
	v_mfma_f32_16x16x32_bf16 v[10:13], v[206:209], v[138:141], v[10:13]
	v_mfma_f32_16x16x32_bf16 v[30:33], v[214:217], v[138:141], v[30:33]
	v_mfma_f32_16x16x32_bf16 v[34:37], v[206:209], v[178:181], v[34:37]
	v_mfma_f32_16x16x32_bf16 v[38:41], v[214:217], v[178:181], v[38:41]
	v_mfma_f32_16x16x32_bf16 v[42:45], v[206:209], v[190:193], v[42:45]
	v_mfma_f32_16x16x32_bf16 v[46:49], v[214:217], v[190:193], v[46:49]
	v_mfma_f32_16x16x32_bf16 v[50:53], v[206:209], v[198:201], v[50:53]
	v_mfma_f32_16x16x32_bf16 v[54:57], v[214:217], v[198:201], v[54:57]
	s_setprio 0
	s_mov_b32 m0, s51
	v_lshl_add_u64 v[6:7], v[6:7], 0, s[14:15]
	s_barrier
	ds_read_b128 v[110:113], v185 offset:49152
	ds_read_b128 v[134:137], v185 offset:50176
	ds_read_b128 v[138:141], v185 offset:51200
	ds_read_b128 v[174:177], v185 offset:52224
	ds_read_b128 v[178:181], v185 offset:53248
	ds_read_b128 v[186:189], v185 offset:54272
	ds_read_b128 v[190:193], v185 offset:55296
	ds_read_b128 v[194:197], v185 offset:56320
	global_load_lds_dwordx4 v[6:7], off
	v_lshl_add_u64 v[6:7], v[8:9], 0, s[14:15]
	s_mov_b32 m0, s49
	s_nop 0
	global_load_lds_dwordx4 v[6:7], off
	s_barrier
	s_waitcnt lgkmcnt(0)
	s_setprio 1
	s_waitcnt lgkmcnt(0)
	v_mfma_f32_16x16x32_bf16 v[6:9], v[102:105], v[110:113], v[142:145]
	v_mfma_f32_16x16x32_bf16 v[14:17], v[102:105], v[190:193], v[14:17]
	v_mfma_f32_16x16x32_bf16 v[18:21], v[126:129], v[190:193], v[18:21]
	v_mfma_f32_16x16x32_bf16 v[6:9], v[106:109], v[134:137], v[6:9]
	v_mfma_f32_16x16x32_bf16 v[142:145], v[126:129], v[110:113], v[146:149]
	v_mfma_f32_16x16x32_bf16 v[146:149], v[102:105], v[138:141], v[154:157]
	v_mfma_f32_16x16x32_bf16 v[154:157], v[126:129], v[138:141], v[158:161]
	v_mfma_f32_16x16x32_bf16 v[158:161], v[102:105], v[178:181], v[162:165]
	v_mfma_f32_16x16x32_bf16 v[162:165], v[126:129], v[178:181], v[166:169]
	v_mfma_f32_16x16x32_bf16 v[14:17], v[106:109], v[194:197], v[14:17]
	v_mfma_f32_16x16x32_bf16 v[18:21], v[130:133], v[194:197], v[18:21]
	v_mfma_f32_16x16x32_bf16 v[142:145], v[130:133], v[134:137], v[142:145]
	v_mfma_f32_16x16x32_bf16 v[146:149], v[106:109], v[174:177], v[146:149]
	v_mfma_f32_16x16x32_bf16 v[154:157], v[130:133], v[174:177], v[154:157]
	v_mfma_f32_16x16x32_bf16 v[158:161], v[106:109], v[186:189], v[158:161]
	v_mfma_f32_16x16x32_bf16 v[162:165], v[130:133], v[186:189], v[162:165]
	s_setprio 0
	s_barrier
	s_mov_b32 m0, s3
	v_lshl_add_u64 v[102:103], s[26:27], 0, v[152:153]
	global_load_lds_dwordx4 v[102:103], off
	v_lshl_add_u64 v[4:5], s[26:27], 0, v[4:5]
	s_mov_b32 m0, s19
	s_nop 0
	global_load_lds_dwordx4 v[4:5], off
	s_waitcnt vmcnt(6)
	s_barrier
	s_setprio 1
	v_mfma_f32_16x16x32_bf16 v[22:25], v[202:205], v[110:113], v[22:25]
	v_mfma_f32_16x16x32_bf16 v[26:29], v[210:213], v[110:113], v[26:29]
	v_mfma_f32_16x16x32_bf16 v[58:61], v[202:205], v[138:141], v[58:61]
	v_mfma_f32_16x16x32_bf16 v[102:105], v[210:213], v[138:141], v[114:117]
	v_mfma_f32_16x16x32_bf16 v[106:109], v[202:205], v[178:181], v[118:121]
	v_mfma_f32_16x16x32_bf16 v[94:97], v[202:205], v[190:193], v[94:97]
	v_mfma_f32_16x16x32_bf16 v[98:101], v[210:213], v[190:193], v[98:101]
	v_mfma_f32_16x16x32_bf16 v[22:25], v[206:209], v[134:137], v[22:25]
	v_mfma_f32_16x16x32_bf16 v[26:29], v[214:217], v[134:137], v[26:29]
	v_mfma_f32_16x16x32_bf16 v[58:61], v[206:209], v[174:177], v[58:61]
	v_mfma_f32_16x16x32_bf16 v[102:105], v[214:217], v[174:177], v[102:105]
	v_mfma_f32_16x16x32_bf16 v[106:109], v[206:209], v[186:189], v[106:109]
	v_mfma_f32_16x16x32_bf16 v[110:113], v[210:213], v[178:181], v[122:125]
	v_mfma_f32_16x16x32_bf16 v[94:97], v[206:209], v[194:197], v[94:97]
	v_mfma_f32_16x16x32_bf16 v[98:101], v[214:217], v[194:197], v[98:101]
	v_mfma_f32_16x16x32_bf16 v[110:113], v[214:217], v[186:189], v[110:113]
	s_setprio 0
	s_add_u32 s24, s24, 0x40180
	s_addc_u32 s25, s25, 0
	s_mov_b32 m0, s50
	v_lshl_add_u64 v[0:1], s[24:25], 0, v[0:1]
	s_barrier
	ds_read_b128 v[114:117], v170
	ds_read_b128 v[118:121], v170 offset:1024
	ds_read_b128 v[122:125], v170 offset:2048
	ds_read_b128 v[126:129], v170 offset:3072
	ds_read_b128 v[130:133], v185
	ds_read_b128 v[134:137], v185 offset:1024
	ds_read_b128 v[138:141], v185 offset:2048
	ds_read_b128 v[166:169], v185 offset:3072
	ds_read_b128 v[174:177], v185 offset:4096
	ds_read_b128 v[178:181], v185 offset:5120
	ds_read_b128 v[186:189], v185 offset:6144
	ds_read_b128 v[190:193], v185 offset:7168
	global_load_lds_dwordx4 v[0:1], off
	v_lshl_add_u64 v[0:1], s[24:25], 0, v[2:3]
	s_mov_b32 m0, s48
	s_nop 0
	global_load_lds_dwordx4 v[0:1], off
	s_barrier
	s_waitcnt lgkmcnt(0)
	s_setprio 1
	s_waitcnt lgkmcnt(0)
	v_mfma_f32_16x16x32_bf16 v[0:3], v[114:117], v[130:133], v[62:65]
	v_mfma_f32_16x16x32_bf16 v[62:65], v[122:125], v[130:133], v[66:69]
	v_mfma_f32_16x16x32_bf16 v[66:69], v[114:117], v[138:141], v[70:73]
	v_mfma_f32_16x16x32_bf16 v[70:73], v[122:125], v[138:141], v[74:77]
	v_mfma_f32_16x16x32_bf16 v[74:77], v[114:117], v[174:177], v[78:81]
	v_mfma_f32_16x16x32_bf16 v[78:81], v[122:125], v[174:177], v[82:85]
	v_mfma_f32_16x16x32_bf16 v[82:85], v[114:117], v[186:189], v[86:89]
	v_mfma_f32_16x16x32_bf16 v[86:89], v[122:125], v[186:189], v[90:93]
	v_mfma_f32_16x16x32_bf16 v[0:3], v[118:121], v[134:137], v[0:3]
	v_mfma_f32_16x16x32_bf16 v[62:65], v[126:129], v[134:137], v[62:65]
	v_mfma_f32_16x16x32_bf16 v[66:69], v[118:121], v[166:169], v[66:69]
	v_mfma_f32_16x16x32_bf16 v[70:73], v[126:129], v[166:169], v[70:73]
	v_mfma_f32_16x16x32_bf16 v[74:77], v[118:121], v[178:181], v[74:77]
	v_mfma_f32_16x16x32_bf16 v[78:81], v[126:129], v[178:181], v[78:81]
	v_mfma_f32_16x16x32_bf16 v[82:85], v[118:121], v[190:193], v[82:85]
	v_mfma_f32_16x16x32_bf16 v[86:89], v[126:129], v[190:193], v[86:89]
	s_setprio 0
	s_barrier
	ds_read_b128 v[90:93], v171
	ds_read_b128 v[194:197], v171 offset:1024
	ds_read_b128 v[198:201], v171 offset:2048
	ds_read_b128 v[202:205], v171 offset:3072
	s_barrier
	s_waitcnt lgkmcnt(0)
	s_setprio 1
	s_waitcnt lgkmcnt(0)
	v_mfma_f32_16x16x32_bf16 v[10:13], v[90:93], v[130:133], v[10:13]
	v_mfma_f32_16x16x32_bf16 v[206:209], v[194:197], v[134:137], v[10:13]
	v_mfma_f32_16x16x32_bf16 v[10:13], v[198:201], v[130:133], v[30:33]
	v_mfma_f32_16x16x32_bf16 v[30:33], v[202:205], v[134:137], v[10:13]
	v_mfma_f32_16x16x32_bf16 v[10:13], v[90:93], v[138:141], v[34:37]
	v_mfma_f32_16x16x32_bf16 v[34:37], v[194:197], v[166:169], v[10:13]
	v_mfma_f32_16x16x32_bf16 v[10:13], v[198:201], v[138:141], v[38:41]
	v_mfma_f32_16x16x32_bf16 v[38:41], v[202:205], v[166:169], v[10:13]
	v_mfma_f32_16x16x32_bf16 v[10:13], v[90:93], v[174:177], v[42:45]
	v_mfma_f32_16x16x32_bf16 v[42:45], v[194:197], v[178:181], v[10:13]
	v_mfma_f32_16x16x32_bf16 v[10:13], v[198:201], v[174:177], v[46:49]
	v_mfma_f32_16x16x32_bf16 v[46:49], v[202:205], v[178:181], v[10:13]
	v_mfma_f32_16x16x32_bf16 v[10:13], v[90:93], v[186:189], v[50:53]
	v_mfma_f32_16x16x32_bf16 v[50:53], v[194:197], v[190:193], v[10:13]
	v_mfma_f32_16x16x32_bf16 v[10:13], v[198:201], v[186:189], v[54:57]
	v_mfma_f32_16x16x32_bf16 v[136:139], v[202:205], v[190:193], v[10:13]
	s_setprio 0
	s_barrier
	s_nop 4
	ds_read_b128 v[10:13], v185 offset:16384
	ds_read_b128 v[54:57], v185 offset:17408
	ds_read_b128 v[130:133], v185 offset:18432
	ds_read_b128 v[166:169], v185 offset:19456
	ds_read_b128 v[174:177], v185 offset:20480
	ds_read_b128 v[178:181], v185 offset:21504
	ds_read_b128 v[186:189], v185 offset:22528
	ds_read_b128 v[190:193], v185 offset:23552
	s_waitcnt vmcnt(4)
	s_barrier
	s_waitcnt lgkmcnt(0)
	s_setprio 1
	s_waitcnt lgkmcnt(0)
	v_mfma_f32_16x16x32_bf16 v[4:7], v[114:117], v[10:13], v[6:9]
	v_mfma_f32_16x16x32_bf16 v[210:213], v[118:121], v[54:57], v[4:7]
	v_mfma_f32_16x16x32_bf16 v[4:7], v[122:125], v[10:13], v[142:145]
	v_mfma_f32_16x16x32_bf16 v[140:143], v[126:129], v[54:57], v[4:7]
	v_mfma_f32_16x16x32_bf16 v[4:7], v[114:117], v[130:133], v[146:149]
	v_mfma_f32_16x16x32_bf16 v[144:147], v[118:121], v[166:169], v[4:7]
	v_mfma_f32_16x16x32_bf16 v[4:7], v[122:125], v[130:133], v[154:157]
	v_mfma_f32_16x16x32_bf16 v[148:151], v[126:129], v[166:169], v[4:7]
	v_mfma_f32_16x16x32_bf16 v[4:7], v[114:117], v[174:177], v[158:161]
	v_mfma_f32_16x16x32_bf16 v[154:157], v[118:121], v[178:181], v[4:7]
	v_mfma_f32_16x16x32_bf16 v[4:7], v[122:125], v[174:177], v[162:165]
	v_mfma_f32_16x16x32_bf16 v[158:161], v[126:129], v[178:181], v[4:7]
	v_mfma_f32_16x16x32_bf16 v[4:7], v[114:117], v[186:189], v[14:17]
	v_mfma_f32_16x16x32_bf16 v[162:165], v[118:121], v[190:193], v[4:7]
	v_mfma_f32_16x16x32_bf16 v[4:7], v[122:125], v[186:189], v[18:21]
	v_mfma_f32_16x16x32_bf16 v[214:217], v[126:129], v[190:193], v[4:7]
	s_setprio 0
	s_setprio 1
	v_mfma_f32_16x16x32_bf16 v[4:7], v[90:93], v[10:13], v[22:25]
	v_mfma_f32_16x16x32_bf16 v[218:221], v[194:197], v[54:57], v[4:7]
	v_mfma_f32_16x16x32_bf16 v[4:7], v[198:201], v[10:13], v[26:29]
	v_mfma_f32_16x16x32_bf16 v[222:225], v[202:205], v[54:57], v[4:7]
	v_mfma_f32_16x16x32_bf16 v[4:7], v[90:93], v[130:133], v[58:61]
	v_mfma_f32_16x16x32_bf16 v[226:229], v[194:197], v[166:169], v[4:7]
	v_mfma_f32_16x16x32_bf16 v[4:7], v[198:201], v[130:133], v[102:105]
	v_mfma_f32_16x16x32_bf16 v[166:169], v[202:205], v[166:169], v[4:7]
	v_mfma_f32_16x16x32_bf16 v[4:7], v[90:93], v[174:177], v[106:109]
	v_mfma_f32_16x16x32_bf16 v[230:233], v[194:197], v[178:181], v[4:7]
	v_mfma_f32_16x16x32_bf16 v[4:7], v[198:201], v[174:177], v[110:113]
	v_mfma_f32_16x16x32_bf16 v[108:111], v[202:205], v[178:181], v[4:7]
	v_mfma_f32_16x16x32_bf16 v[4:7], v[90:93], v[186:189], v[94:97]
	v_mfma_f32_16x16x32_bf16 v[112:115], v[194:197], v[190:193], v[4:7]
	v_mfma_f32_16x16x32_bf16 v[4:7], v[198:201], v[186:189], v[98:101]
	v_mfma_f32_16x16x32_bf16 v[174:177], v[202:205], v[190:193], v[4:7]
	s_setprio 0
	s_barrier
	ds_read_b128 v[16:19], v234
	ds_read_b128 v[20:23], v234 offset:1024
	ds_read_b128 v[90:93], v234 offset:2048
	ds_read_b128 v[94:97], v234 offset:3072
	ds_read_b128 v[24:27], v185 offset:32768
	ds_read_b128 v[54:57], v185 offset:33792
	ds_read_b128 v[58:61], v185 offset:34816
	ds_read_b128 v[178:181], v185 offset:35840
	ds_read_b128 v[186:189], v185 offset:36864
	ds_read_b128 v[190:193], v185 offset:37888
	ds_read_b128 v[194:197], v185 offset:38912
	ds_read_b128 v[198:201], v185 offset:39936
	s_waitcnt vmcnt(2)
	s_barrier
	s_waitcnt lgkmcnt(0)
	s_setprio 1
	s_waitcnt lgkmcnt(0)
	v_mfma_f32_16x16x32_bf16 v[0:3], v[16:19], v[24:27], v[0:3]
	v_mfma_f32_16x16x32_bf16 v[104:107], v[20:23], v[54:57], v[0:3]
	v_mfma_f32_16x16x32_bf16 v[0:3], v[90:93], v[24:27], v[62:65]
	v_mfma_f32_16x16x32_bf16 v[100:103], v[94:97], v[54:57], v[0:3]
	v_mfma_f32_16x16x32_bf16 v[0:3], v[16:19], v[58:61], v[66:69]
	v_mfma_f32_16x16x32_bf16 v[120:123], v[20:23], v[178:181], v[0:3]
	v_mfma_f32_16x16x32_bf16 v[0:3], v[90:93], v[58:61], v[70:73]
	v_mfma_f32_16x16x32_bf16 v[116:119], v[94:97], v[178:181], v[0:3]
	v_mfma_f32_16x16x32_bf16 v[0:3], v[16:19], v[186:189], v[74:77]
	v_mfma_f32_16x16x32_bf16 v[8:11], v[20:23], v[190:193], v[0:3]
	v_mfma_f32_16x16x32_bf16 v[0:3], v[90:93], v[186:189], v[78:81]
	v_mfma_f32_16x16x32_bf16 v[12:15], v[94:97], v[190:193], v[0:3]
	v_mfma_f32_16x16x32_bf16 v[0:3], v[16:19], v[194:197], v[82:85]
	v_mfma_f32_16x16x32_bf16 v[4:7], v[90:93], v[194:197], v[86:89]
	v_mfma_f32_16x16x32_bf16 v[0:3], v[20:23], v[198:201], v[0:3]
	v_mfma_f32_16x16x32_bf16 v[4:7], v[94:97], v[198:201], v[4:7]
	s_setprio 0
	s_barrier
	ds_read_b128 v[68:71], v235
	ds_read_b128 v[72:75], v235 offset:1024
	ds_read_b128 v[202:205], v235 offset:2048
	ds_read_b128 v[234:237], v235 offset:3072
	s_waitcnt vmcnt(0)
	s_barrier
	s_waitcnt lgkmcnt(0)
	s_setprio 1
	s_waitcnt lgkmcnt(0)
	v_mfma_f32_16x16x32_bf16 v[62:65], v[68:71], v[24:27], v[206:209]
	v_mfma_f32_16x16x32_bf16 v[24:27], v[202:205], v[24:27], v[30:33]
	v_mfma_f32_16x16x32_bf16 v[124:127], v[234:237], v[54:57], v[24:27]
	v_mfma_f32_16x16x32_bf16 v[24:27], v[68:71], v[58:61], v[34:37]
	v_mfma_f32_16x16x32_bf16 v[128:131], v[72:75], v[178:181], v[24:27]
	v_mfma_f32_16x16x32_bf16 v[24:27], v[202:205], v[58:61], v[38:41]
	v_mfma_f32_16x16x32_bf16 v[132:135], v[72:75], v[54:57], v[62:65]
	v_mfma_f32_16x16x32_bf16 v[56:59], v[234:237], v[178:181], v[24:27]
	v_mfma_f32_16x16x32_bf16 v[24:27], v[68:71], v[186:189], v[42:45]
	v_mfma_f32_16x16x32_bf16 v[40:43], v[72:75], v[190:193], v[24:27]
	v_mfma_f32_16x16x32_bf16 v[24:27], v[202:205], v[186:189], v[46:49]
	v_mfma_f32_16x16x32_bf16 v[44:47], v[234:237], v[190:193], v[24:27]
	v_mfma_f32_16x16x32_bf16 v[24:27], v[68:71], v[194:197], v[50:53]
	v_mfma_f32_16x16x32_bf16 v[28:31], v[202:205], v[194:197], v[136:139]
	v_mfma_f32_16x16x32_bf16 v[24:27], v[72:75], v[198:201], v[24:27]
	v_mfma_f32_16x16x32_bf16 v[28:31], v[234:237], v[198:201], v[28:31]
	s_setprio 0
	s_barrier
	ds_read_b128 v[76:79], v185 offset:49152
	ds_read_b128 v[80:83], v185 offset:50176
	ds_read_b128 v[136:139], v185 offset:51200
	ds_read_b128 v[178:181], v185 offset:52224
	ds_read_b128 v[186:189], v185 offset:53248
	ds_read_b128 v[190:193], v185 offset:54272
	ds_read_b128 v[194:197], v185 offset:55296
	ds_read_b128 v[198:201], v185 offset:56320
	s_barrier
	s_waitcnt lgkmcnt(0)
	s_setprio 1
	s_waitcnt lgkmcnt(0)
	v_mfma_f32_16x16x32_bf16 v[32:35], v[16:19], v[76:79], v[210:213]
	v_mfma_f32_16x16x32_bf16 v[60:63], v[20:23], v[80:83], v[32:35]
	v_mfma_f32_16x16x32_bf16 v[32:35], v[90:93], v[76:79], v[140:143]
	v_mfma_f32_16x16x32_bf16 v[64:67], v[94:97], v[80:83], v[32:35]
	v_mfma_f32_16x16x32_bf16 v[32:35], v[16:19], v[136:139], v[144:147]
	v_mfma_f32_16x16x32_bf16 v[48:51], v[20:23], v[178:181], v[32:35]
	v_mfma_f32_16x16x32_bf16 v[32:35], v[90:93], v[136:139], v[148:151]
	v_mfma_f32_16x16x32_bf16 v[52:55], v[94:97], v[178:181], v[32:35]
	v_mfma_f32_16x16x32_bf16 v[32:35], v[16:19], v[186:189], v[154:157]
	v_mfma_f32_16x16x32_bf16 v[16:19], v[16:19], v[194:197], v[162:165]
	v_mfma_f32_16x16x32_bf16 v[32:35], v[20:23], v[190:193], v[32:35]
	v_mfma_f32_16x16x32_bf16 v[36:39], v[90:93], v[186:189], v[158:161]
	v_mfma_f32_16x16x32_bf16 v[16:19], v[20:23], v[198:201], v[16:19]
	v_mfma_f32_16x16x32_bf16 v[20:23], v[90:93], v[194:197], v[214:217]
	v_mfma_f32_16x16x32_bf16 v[36:39], v[94:97], v[190:193], v[36:39]
	v_mfma_f32_16x16x32_bf16 v[20:23], v[94:97], v[198:201], v[20:23]
	s_setprio 0
	s_setprio 1
	v_mfma_f32_16x16x32_bf16 v[84:87], v[68:71], v[76:79], v[218:221]
	v_mfma_f32_16x16x32_bf16 v[76:79], v[202:205], v[76:79], v[222:225]
	v_mfma_f32_16x16x32_bf16 v[96:99], v[234:237], v[80:83], v[76:79]
	v_mfma_f32_16x16x32_bf16 v[76:79], v[68:71], v[136:139], v[226:229]
	v_mfma_f32_16x16x32_bf16 v[92:95], v[72:75], v[80:83], v[84:87]
	v_mfma_f32_16x16x32_bf16 v[84:87], v[72:75], v[178:181], v[76:79]
	v_mfma_f32_16x16x32_bf16 v[76:79], v[202:205], v[136:139], v[166:169]
	v_mfma_f32_16x16x32_bf16 v[88:91], v[234:237], v[178:181], v[76:79]
	v_mfma_f32_16x16x32_bf16 v[76:79], v[68:71], v[186:189], v[230:233]
	v_mfma_f32_16x16x32_bf16 v[68:71], v[68:71], v[194:197], v[112:115]
	v_mfma_f32_16x16x32_bf16 v[76:79], v[72:75], v[190:193], v[76:79]
	v_mfma_f32_16x16x32_bf16 v[80:83], v[202:205], v[186:189], v[108:111]
	v_mfma_f32_16x16x32_bf16 v[68:71], v[72:75], v[198:201], v[68:71]
	v_mfma_f32_16x16x32_bf16 v[72:75], v[202:205], v[194:197], v[174:177]
	v_mfma_f32_16x16x32_bf16 v[80:83], v[234:237], v[190:193], v[80:83]
	v_mfma_f32_16x16x32_bf16 v[72:75], v[234:237], v[198:201], v[72:75]
	s_setprio 0
	s_cmpk_gt_u32 s2, 0xff
	s_barrier
	s_cbranch_scc1 .LBB0_659
	s_barrier

.LBB0_677:
	s_or_b64 exec, exec, s[0:1]
	v_add_u32_e32 v46, 0xc0, v152
	s_waitcnt lgkmcnt(1)
	ds_read2st64_b32 v[44:45], v46 offset0:2 offset1:6
	s_waitcnt lgkmcnt(1)
	ds_read2st64_b32 v[46:47], v46 offset0:10 offset1:14
	ds_read_b32 v48, v174 offset:704
	ds_read_b32 v49, v175 offset:704
	ds_read_b32 v50, v176 offset:704
	s_waitcnt lgkmcnt(4)
	v_add_f32_e32 v44, v44, v45
	s_waitcnt lgkmcnt(3)
	v_add_f32_e32 v44, v44, v46
	v_add_f32_e32 v44, v44, v47
	s_waitcnt lgkmcnt(1)
	v_fmac_f32_e32 v44, v48, v49
	s_waitcnt lgkmcnt(0)
	v_max_f32_e32 v45, v50, v50
	v_max_f32_e64 v44, |v44|, v45
	v_rcp_f32_e32 v44, v44
	v_and_b32_e32 v50, 0xffff0000, v86
	v_mul_f32_e32 v50, 0xbfb8aa3b, v50
	v_exp_f32_e32 v51, v50
	v_pk_mul_f32 v[42:43], v[42:43], v[44:45] op_sel_hi:[1,0]
	v_pk_mul_f32 v[40:41], v[40:41], v[44:45] op_sel_hi:[1,0]
	v_pk_mul_f32 v[46:47], v[2:3], v[44:45] op_sel_hi:[1,0]
	v_pk_mul_f32 v[48:49], v[0:1], v[44:45] op_sel_hi:[1,0]
	v_lshlrev_b32_e32 v45, 16, v86
	v_mul_f32_e32 v45, 0xbfb8aa3b, v45
	v_exp_f32_e32 v45, v45
	v_lshlrev_b32_e32 v2, 16, v84
	v_and_b32_e32 v3, 0xffff0000, v84
	v_mul_f32_e32 v2, 0xbfb8aa3b, v2
	v_add_f32_e32 v45, 1.0, v45
	v_rcp_f32_e32 v50, v45
	v_add_f32_e32 v45, 1.0, v51
	v_lshlrev_b32_e32 v51, 16, v87
	v_mul_f32_e32 v51, 0xbfb8aa3b, v51
	v_exp_f32_e32 v52, v51
	v_and_b32_e32 v51, 0xffff0000, v87
	v_mul_f32_e32 v51, 0xbfb8aa3b, v51
	v_mul_f32_e32 v3, 0xbfb8aa3b, v3
	v_exp_f32_e32 v53, v51
	v_exp_f32_e32 v2, v2
	v_exp_f32_e32 v3, v3
	v_rcp_f32_e32 v51, v45
	v_add_f32_e32 v45, 1.0, v52
	v_rcp_f32_e32 v52, v45
	v_add_f32_e32 v45, 1.0, v53
	v_add_f32_e32 v0, 1.0, v2
	v_add_f32_e32 v1, 1.0, v3
	v_lshlrev_b32_e32 v2, 16, v85
	v_and_b32_e32 v3, 0xffff0000, v85
	v_rcp_f32_e32 v53, v45
	v_pk_mul_f32 v[84:85], v[50:51], v[48:49]
	v_pk_mul_f32 v[38:39], v[38:39], v[44:45] op_sel_hi:[1,0]
	v_pk_mul_f32 v[36:37], v[36:37], v[44:45] op_sel_hi:[1,0]
	v_pk_mul_f32 v[34:35], v[34:35], v[44:45] op_sel_hi:[1,0]
	v_lshlrev_b32_e32 v45, 16, v80
	v_and_b32_e32 v50, 0xffff0000, v80
	v_mul_f32_e32 v45, 0xbfb8aa3b, v45
	v_mul_f32_e32 v50, 0xbfb8aa3b, v50
	v_exp_f32_e32 v45, v45
	v_exp_f32_e32 v50, v50
	v_mul_f32_e32 v2, 0xbfb8aa3b, v2
	v_mul_f32_e32 v3, 0xbfb8aa3b, v3
	v_pk_mul_f32 v[76:77], v[52:53], v[46:47]
	v_pk_mul_f32 v[32:33], v[32:33], v[44:45] op_sel_hi:[1,0]
	v_add_f32_e32 v44, 1.0, v45
	v_add_f32_e32 v45, 1.0, v50
	v_lshlrev_b32_e32 v50, 16, v81
	v_and_b32_e32 v51, 0xffff0000, v81
	v_lshlrev_b32_e32 v52, 16, v82
	v_and_b32_e32 v53, 0xffff0000, v82
	v_exp_f32_e32 v2, v2
	v_exp_f32_e32 v3, v3
	v_mul_f32_e32 v50, 0xbfb8aa3b, v50
	v_mul_f32_e32 v51, 0xbfb8aa3b, v51
	v_mul_f32_e32 v52, 0xbfb8aa3b, v52
	v_mul_f32_e32 v53, 0xbfb8aa3b, v53
	v_exp_f32_e32 v50, v50
	v_exp_f32_e32 v51, v51
	v_exp_f32_e32 v52, v52
	v_exp_f32_e32 v53, v53
	v_lshlrev_b32_e32 v54, 16, v83
	v_and_b32_e32 v55, 0xffff0000, v83
	v_rcp_f32_e32 v0, v0
	v_rcp_f32_e32 v1, v1
	v_add_f32_e32 v2, 1.0, v2
	v_add_f32_e32 v3, 1.0, v3
	v_mul_f32_e32 v54, 0xbfb8aa3b, v54
	v_mul_f32_e32 v55, 0xbfb8aa3b, v55
	v_rcp_f32_e32 v2, v2
	v_rcp_f32_e32 v3, v3
	v_rcp_f32_e32 v44, v44
	v_rcp_f32_e32 v45, v45
	v_add_f32_e32 v50, 1.0, v50
	v_add_f32_e32 v51, 1.0, v51
	v_add_f32_e32 v52, 1.0, v52
	v_add_f32_e32 v53, 1.0, v53
	v_exp_f32_e32 v54, v54
	v_exp_f32_e32 v55, v55
	v_rcp_f32_e32 v50, v50
	v_rcp_f32_e32 v51, v51
	v_rcp_f32_e32 v52, v52
	v_rcp_f32_e32 v53, v53
	v_pk_mul_f32 v[0:1], v[0:1], v[40:41]
	v_pk_mul_f32 v[2:3], v[2:3], v[42:43]
	v_add_f32_e32 v40, v0, v1
	v_add_f32_e32 v54, 1.0, v54
	v_add_f32_e32 v55, 1.0, v55
	v_pk_mul_f32 v[82:83], v[44:45], v[36:37]
	v_add_f32_e32 v40, v2, v40
	v_rcp_f32_e32 v54, v54
	v_rcp_f32_e32 v55, v55
	v_pk_mul_f32 v[80:81], v[50:51], v[38:39]
	v_pk_mul_f32 v[74:75], v[52:53], v[32:33]
	v_add_f32_e32 v32, v82, v83
	v_add_f32_e32 v40, v3, v40
	v_add_f32_e32 v32, v80, v32
	v_add_f32_e32 v40, v84, v40
	v_add_f32_e32 v32, v81, v32
	v_add_f32_e32 v40, v85, v40
	v_add_f32_e32 v32, v74, v32
	v_add_f32_e32 v40, v76, v40
	v_pk_mul_f32 v[72:73], v[54:55], v[34:35]
	v_add_f32_e32 v32, v75, v32
	v_add_f32_e32 v40, v77, v40
	v_add_f32_e32 v32, v72, v32
	v_add_f32_e32 v56, 0, v40
	v_add_f32_e32 v32, v73, v32
	v_pk_mul_f32 v[40:41], v[0:1], v[0:1]
	v_add_f32_e32 v44, v32, v56
	v_pk_mul_f32 v[32:33], v[82:83], v[82:83]
	v_pk_mul_f32 v[42:43], v[2:3], v[2:3]
	v_pk_mul_f32 v[34:35], v[80:81], v[80:81]
	v_add_f32_e32 v32, v32, v33
	v_add_f32_e32 v33, v40, v41
	v_add_f32_e32 v32, v34, v32
	v_add_f32_e32 v33, v42, v33
	v_pk_mul_f32 v[46:47], v[84:85], v[84:85]
	v_pk_mul_f32 v[36:37], v[74:75], v[74:75]
	v_add_f32_e32 v32, v35, v32
	v_add_f32_e32 v33, v43, v33
	v_add_f32_e32 v32, v36, v32
	v_add_f32_e32 v33, v46, v33
	v_pk_mul_f32 v[48:49], v[76:77], v[76:77]
	v_pk_mul_f32 v[38:39], v[72:73], v[72:73]
	v_add_f32_e32 v32, v37, v32
	v_add_f32_e32 v33, v47, v33
	v_add_f32_e32 v32, v38, v32
	v_add_f32_e32 v33, v48, v33
	v_add_f32_e32 v32, v39, v32
	v_add_f32_e32 v33, v49, v33
	v_add_f32_e32 v35, v33, v32
	ds_bpermute_b32 v34, v172, v44
	ds_bpermute_b32 v36, v172, v35
	s_lshl_b64 s[0:1], s[20:21], 10
	s_waitcnt lgkmcnt(1)
	v_add_f32_e32 v32, v44, v34
	s_waitcnt lgkmcnt(0)
	v_add_f32_e32 v34, v35, v36
	ds_bpermute_b32 v33, v173, v32
	ds_bpermute_b32 v35, v173, v34
	s_and_saveexec_b64 s[20:21], vcc
	s_cbranch_execz .LBB0_614
	s_waitcnt lgkmcnt(1)
	v_add_f32_e32 v32, v32, v33
	s_waitcnt lgkmcnt(0)
	v_add_f32_e32 v33, v34, v35
	v_add_u32_e32 v34, 0xc0, v177
	ds_write2st64_b32 v34, v32, v33 offset0:2 offset1:18
	s_branch .LBB0_614
	s_nop 0
	s_nop 0
	s_nop 0
	s_nop 0
	s_nop 0
	s_nop 0
	s_nop 0
	s_nop 0
	s_nop 0
	s_nop 0
	s_nop 0
	s_nop 0
	s_nop 0
	s_nop 0
	s_nop 0
	s_nop 0
	s_nop 0
	s_nop 0
	s_nop 0
	s_nop 0
	s_nop 0
	s_nop 0
	s_nop 0
	s_nop 0
	s_nop 0
	s_nop 0
	s_nop 0
	s_nop 0
	s_nop 0
	s_nop 0
	s_nop 0
	s_nop 0
	s_nop 0
	s_nop 0
	s_nop 0
	s_nop 0
	s_nop 0
	s_nop 0
	s_nop 0
	s_nop 0
	s_nop 0
	s_nop 0
	s_nop 0
	s_nop 0
	s_nop 0
	s_nop 0
	s_nop 0
	s_nop 0
	s_nop 0
	s_nop 0
	s_nop 0
	s_nop 0
	s_nop 0
	s_nop 0
	s_nop 0
	s_nop 0
	s_nop 0
	s_nop 0
	s_nop 0
	s_nop 0
	s_nop 0
	s_nop 0
	s_nop 0
	s_nop 0
	s_nop 0
	s_nop 0
	s_nop 0
	s_nop 0
	s_nop 0
	s_nop 0
	s_nop 0
	s_nop 0
	s_nop 0
	s_nop 0
